# attention bf16 output rows stored as 4x dwordx4 per lane (half-wave permlane32 swaps pair 8-byte pieces) in both DK=64 and DK=96 epilogues
# speedup vs baseline: 1.1144x; 1.0043x over previous
.LBB0_308:
	v_readlane_b32 s2, v251, 52
	v_lshlrev_b64 v[46:47], 11, v[84:85]
	v_readlane_b32 s3, v251, 53
	v_pk_mul_f32 v[22:23], v[22:23], v[44:45]
	v_pk_mul_f32 v[24:25], v[24:25], v[44:45]
	v_pk_mul_f32 v[26:27], v[26:27], v[44:45]
	v_pk_mul_f32 v[28:29], v[28:29], v[44:45]
	v_pk_mul_f32 v[30:31], v[30:31], v[44:45]
	v_pk_mul_f32 v[32:33], v[32:33], v[44:45]
	v_pk_mul_f32 v[34:35], v[34:35], v[44:45]
	v_pk_mul_f32 v[6:7], v[6:7], v[44:45]
	v_pk_mul_f32 v[8:9], v[8:9], v[44:45]
	v_pk_mul_f32 v[10:11], v[10:11], v[44:45]
	v_pk_mul_f32 v[12:13], v[12:13], v[44:45]
	v_pk_mul_f32 v[14:15], v[14:15], v[44:45]
	v_pk_mul_f32 v[16:17], v[16:17], v[44:45]
	v_pk_mul_f32 v[18:19], v[18:19], v[44:45]
	v_lshl_add_u64 v[46:47], s[2:3], 0, v[46:47]
	v_cvt_pk_bf16_f32 v48, v40, v41
	v_cvt_pk_bf16_f32 v49, v22, v23
	v_cvt_pk_bf16_f32 v50, v24, v25
	v_cvt_pk_bf16_f32 v51, v26, v27
	v_cvt_pk_bf16_f32 v52, v28, v29
	v_cvt_pk_bf16_f32 v53, v30, v31
	v_cvt_pk_bf16_f32 v54, v32, v33
	v_cvt_pk_bf16_f32 v55, v34, v35
	v_cvt_pk_bf16_f32 v56, v36, v37
	v_cvt_pk_bf16_f32 v57, v6, v7
	v_cvt_pk_bf16_f32 v58, v8, v9
	v_cvt_pk_bf16_f32 v59, v10, v11
	v_cvt_pk_bf16_f32 v60, v12, v13
	v_cvt_pk_bf16_f32 v61, v14, v15
	v_cvt_pk_bf16_f32 v62, v16, v17
	v_cvt_pk_bf16_f32 v63, v18, v19
	v_lshl_add_u64 v[46:47], v[2:3], 2, v[46:47]
	s_nop 1
	v_permlane32_swap_b32 v48, v50
	v_permlane32_swap_b32 v49, v51
	v_permlane32_swap_b32 v52, v54
	v_permlane32_swap_b32 v53, v55
	v_permlane32_swap_b32 v56, v58
	v_permlane32_swap_b32 v57, v59
	v_permlane32_swap_b32 v60, v62
	v_permlane32_swap_b32 v61, v63
	s_nop 1
	global_store_dwordx4 v[46:47], v[48:51], off
	global_store_dwordx4 v[46:47], v[52:55], off offset:32
	global_store_dwordx4 v[46:47], v[56:59], off offset:64
	global_store_dwordx4 v[46:47], v[60:63], off offset:96

.LBB0_386:
	v_xor_b32_e32 v2, 32, v229
	v_cmp_lt_i32_e32 vcc, v2, v231
	v_mov_b32_e32 v99, v3
	s_waitcnt vmcnt(0) lgkmcnt(0)
	v_cndmask_b32_e32 v2, v229, v2, vcc
	v_lshlrev_b32_e32 v2, 2, v2
	ds_bpermute_b32 v2, v2, v36
	s_barrier
	s_waitcnt lgkmcnt(0)
	s_mov_b64 s[28:29], 0
	v_add_f32_e32 v2, v36, v2
	v_div_scale_f32 v36, s[2:3], v2, v2, 1.0
	v_rcp_f32_e32 v37, v36
	v_div_scale_f32 v38, vcc, 1.0, v2, 1.0
	v_readlane_b32 s2, v251, 52
	v_fma_f32 v39, -v36, v37, 1.0
	v_fmac_f32_e32 v37, v39, v37
	v_mul_f32_e32 v39, v38, v37
	v_fma_f32 v40, -v36, v39, v38
	v_fmac_f32_e32 v39, v40, v37
	v_fma_f32 v36, -v36, v39, v38
	v_div_fmas_f32 v36, v36, v37, v39
	v_div_fixup_f32 v2, v36, v2, 1.0
	v_lshlrev_b64 v[36:37], 11, v[92:93]
	v_readlane_b32 s3, v251, 53
	v_pk_mul_f32 v[4:5], v[4:5], v[2:3] op_sel_hi:[1,0]
	v_pk_mul_f32 v[6:7], v[6:7], v[2:3] op_sel_hi:[1,0]
	v_pk_mul_f32 v[8:9], v[8:9], v[2:3] op_sel_hi:[1,0]
	v_pk_mul_f32 v[10:11], v[10:11], v[2:3] op_sel_hi:[1,0]
	v_pk_mul_f32 v[12:13], v[12:13], v[2:3] op_sel_hi:[1,0]
	v_pk_mul_f32 v[14:15], v[14:15], v[2:3] op_sel_hi:[1,0]
	v_pk_mul_f32 v[16:17], v[16:17], v[2:3] op_sel_hi:[1,0]
	v_pk_mul_f32 v[18:19], v[18:19], v[2:3] op_sel_hi:[1,0]
	v_pk_mul_f32 v[20:21], v[20:21], v[2:3] op_sel_hi:[1,0]
	v_pk_mul_f32 v[22:23], v[22:23], v[2:3] op_sel_hi:[1,0]
	v_pk_mul_f32 v[24:25], v[24:25], v[2:3] op_sel_hi:[1,0]
	v_pk_mul_f32 v[26:27], v[26:27], v[2:3] op_sel_hi:[1,0]
	v_pk_mul_f32 v[28:29], v[28:29], v[2:3] op_sel_hi:[1,0]
	v_pk_mul_f32 v[30:31], v[30:31], v[2:3] op_sel_hi:[1,0]
	v_pk_mul_f32 v[32:33], v[32:33], v[2:3] op_sel_hi:[1,0]
	v_pk_mul_f32 v[34:35], v[34:35], v[2:3] op_sel_hi:[1,0]
	v_lshl_add_u64 v[36:37], s[2:3], 0, v[36:37]
	v_cvt_pk_bf16_f32 v40, v20, v21
	v_cvt_pk_bf16_f32 v41, v22, v23
	v_cvt_pk_bf16_f32 v42, v24, v25
	v_cvt_pk_bf16_f32 v43, v26, v27
	v_cvt_pk_bf16_f32 v44, v28, v29
	v_cvt_pk_bf16_f32 v45, v30, v31
	v_cvt_pk_bf16_f32 v46, v32, v33
	v_cvt_pk_bf16_f32 v47, v34, v35
	v_cvt_pk_bf16_f32 v48, v4, v5
	v_cvt_pk_bf16_f32 v49, v6, v7
	v_cvt_pk_bf16_f32 v50, v8, v9
	v_cvt_pk_bf16_f32 v51, v10, v11
	v_cvt_pk_bf16_f32 v52, v12, v13
	v_cvt_pk_bf16_f32 v53, v14, v15
	v_cvt_pk_bf16_f32 v54, v16, v17
	v_cvt_pk_bf16_f32 v55, v18, v19
	v_lshl_add_u64 v[36:37], v[98:99], 1, v[36:37]
	s_nop 1
	v_permlane32_swap_b32 v40, v42
	v_permlane32_swap_b32 v41, v43
	v_permlane32_swap_b32 v44, v46
	v_permlane32_swap_b32 v45, v47
	v_permlane32_swap_b32 v48, v50
	v_permlane32_swap_b32 v49, v51
	v_permlane32_swap_b32 v52, v54
	v_permlane32_swap_b32 v53, v55
	s_nop 1
	global_store_dwordx4 v[36:37], v[40:43], off
	global_store_dwordx4 v[36:37], v[44:47], off offset:32
	global_store_dwordx4 v[36:37], v[48:51], off offset:64
	global_store_dwordx4 v[36:37], v[52:55], off offset:96
	s_barrier
